# v18 + P15->P18 seam: grid barrier replaced by a 64-workgroup per-batch barrier (NSA units of batch b and w_o row groups 2b, 2b+1 run on the same 64 workgroups)
# speedup vs baseline: 1.0010x; 1.0002x over previous
.LBB0_2070:
	s_load_dwordx2 s[2:3], s[0:1], 0x310
	s_waitcnt lgkmcnt(0)
	s_cmp_gt_u32 s3, 16
	s_cselect_b64 s[2:3], -1, 0
	s_and_b64 s[2:3], s[4:5], s[2:3]
	s_andn2_b64 vcc, exec, s[2:3]
	s_cbranch_vccnz .LBB0_2124
	s_cmpk_lg_i32 s80, 0x100
	s_cbranch_scc1 .Lgb_orig_9
	s_waitcnt vmcnt(0)
	s_barrier
	s_and_saveexec_b64 s[4:5], s[86:87]
	s_cbranch_execz .Lgb_done_9
	buffer_wbl2 sc1
	s_waitcnt vmcnt(0)
	s_and_b32 s2, s76, 6
	s_lshl_b32 s2, s2, 8
	s_add_u32 s2, s74, s2
	s_addc_u32 s3, s75, 0
	v_mov_b32_e32 v2, 0x6000
	v_mov_b32_e32 v3, 1
	v_mov_b32_e32 v5, 0
	global_atomic_add v2, v3, s[2:3]
.Lgb_spin_9:
	global_load_dword v4, v2, s[2:3] sc1
	v_add_u32_e32 v5, 1, v5
	s_waitcnt vmcnt(0)
	v_cmp_gt_u32_e32 vcc, 64, v4
	s_cbranch_vccz .Lgb_out_9
	s_sleep 1
	v_cmp_gt_u32_e32 vcc, 0x8000, v5
	s_cbranch_vccnz .Lgb_spin_9

.Lgb_orig_9:
	s_waitcnt vmcnt(0)
	s_waitcnt vmcnt(0)
	s_barrier
	s_and_saveexec_b64 s[4:5], s[86:87]
	s_cbranch_execz .LBB0_2123
	s_add_i32 s2, 0, 0x25f00
	v_mov_b32_e32 v2, s2
	s_waitcnt vmcnt(0) expcnt(0) lgkmcnt(0)
	ds_read_b32 v4, v2
	s_add_i32 s2, 0, 0x25f04
	v_mov_b32_e32 v2, s2
	ds_read_b32 v2, v2
	s_waitcnt lgkmcnt(1)
	v_cmp_ne_u32_e32 vcc, 0, v4
	s_cbranch_vccnz .LBB0_2087
	v_readlane_b32 s6, v250, 0
	v_readlane_b32 s7, v250, 1
	s_load_dwordx2 s[2:3], s[6:7], 0x4
	s_add_u32 s6, s74, 0x1000
	s_addc_u32 s7, s75, 0
	s_add_u32 s8, s74, 0x1100
	s_addc_u32 s9, s75, 0
	s_add_u32 s10, s74, 0x1200
	s_addc_u32 s11, s75, 0
	s_waitcnt lgkmcnt(0)
	s_mul_i32 s2, s2, s80
	s_add_u32 s12, s74, 0x1300
	s_mul_i32 s2, s2, s3
	s_addc_u32 s13, s75, 0
	s_mov_b32 s3, 1
	v_mov_b32_e32 v18, 0
	s_branch .LBB0_2075
